# EpiProj gate path: packed f32 sigmoid with bias pre-scaled by -log2e (pk_fma/pk_add), 16 blocks
# speedup vs baseline: 1.0000x; 1.0000x over previous
.LBB0_147:
	s_and_b64 vcc, exec, s[40:41]
	s_cbranch_vccnz .LBB0_149
	s_waitcnt vmcnt(0) lgkmcnt(0)
	s_mov_b32 s98, 0xbfb8aa3b
	s_mov_b32 s99, 0xbfb8aa3b
	v_pk_mul_f32 v[40:41], v[40:41], s[98:99]
	v_pk_mul_f32 v[42:43], v[42:43], s[98:99]
	v_pk_mul_f32 v[44:45], v[44:45], s[98:99]
	v_pk_mul_f32 v[46:47], v[46:47], s[98:99]
	v_pk_mul_f32 v[56:57], v[56:57], s[98:99]
	v_pk_mul_f32 v[58:59], v[58:59], s[98:99]
	v_pk_mul_f32 v[60:61], v[60:61], s[98:99]
	v_pk_mul_f32 v[62:63], v[62:63], s[98:99]
	v_pk_fma_f32 v[166:167], v[166:167], s[98:99], v[62:63]
	v_pk_fma_f32 v[232:233], v[232:233], s[98:99], v[58:59]
	v_pk_fma_f32 v[234:235], v[234:235], s[98:99], v[60:61]
	v_pk_fma_f32 v[236:237], v[236:237], s[98:99], v[56:57]
	v_exp_f32_e32 v166, v166
	v_exp_f32_e32 v167, v167
	v_exp_f32_e32 v232, v232
	v_exp_f32_e32 v233, v233
	v_exp_f32_e32 v234, v234
	v_exp_f32_e32 v235, v235
	v_exp_f32_e32 v236, v236
	v_exp_f32_e32 v237, v237
	v_pk_add_f32 v[166:167], v[166:167], 1.0 op_sel_hi:[1,0]
	v_pk_add_f32 v[232:233], v[232:233], 1.0 op_sel_hi:[1,0]
	v_pk_add_f32 v[234:235], v[234:235], 1.0 op_sel_hi:[1,0]
	v_pk_add_f32 v[236:237], v[236:237], 1.0 op_sel_hi:[1,0]
	v_rcp_f32_e32 v166, v166
	v_rcp_f32_e32 v167, v167
	v_rcp_f32_e32 v232, v232
	v_rcp_f32_e32 v233, v233
	v_rcp_f32_e32 v234, v234
	v_rcp_f32_e32 v235, v235
	v_rcp_f32_e32 v236, v236
	v_rcp_f32_e32 v237, v237

.LBB0_157:
	s_and_b64 vcc, exec, s[40:41]
	s_cbranch_vccnz .LBB0_159
	s_waitcnt lgkmcnt(0)
	v_pk_fma_f32 v[150:151], v[150:151], s[98:99], v[46:47]
	v_pk_fma_f32 v[162:163], v[162:163], s[98:99], v[42:43]
	v_pk_fma_f32 v[164:165], v[164:165], s[98:99], v[44:45]
	v_pk_fma_f32 v[166:167], v[166:167], s[98:99], v[40:41]
	v_exp_f32_e32 v150, v150
	v_exp_f32_e32 v151, v151
	v_exp_f32_e32 v162, v162
	v_exp_f32_e32 v163, v163
	v_exp_f32_e32 v164, v164
	v_exp_f32_e32 v165, v165
	v_exp_f32_e32 v166, v166
	v_exp_f32_e32 v167, v167
	v_pk_add_f32 v[150:151], v[150:151], 1.0 op_sel_hi:[1,0]
	v_pk_add_f32 v[162:163], v[162:163], 1.0 op_sel_hi:[1,0]
	v_pk_add_f32 v[164:165], v[164:165], 1.0 op_sel_hi:[1,0]
	v_pk_add_f32 v[166:167], v[166:167], 1.0 op_sel_hi:[1,0]
	v_rcp_f32_e32 v150, v150
	v_rcp_f32_e32 v151, v151
	v_rcp_f32_e32 v162, v162
	v_rcp_f32_e32 v163, v163
	v_rcp_f32_e32 v164, v164
	v_rcp_f32_e32 v165, v165
	v_rcp_f32_e32 v166, v166
	v_rcp_f32_e32 v167, v167

.LBB0_167:
	s_and_b64 vcc, exec, s[40:41]
	s_cbranch_vccnz .LBB0_169
	s_waitcnt lgkmcnt(0)
	v_pk_fma_f32 v[144:145], v[144:145], s[98:99], v[62:63]
	v_pk_fma_f32 v[146:147], v[146:147], s[98:99], v[58:59]
	v_pk_fma_f32 v[148:149], v[148:149], s[98:99], v[60:61]
	v_pk_fma_f32 v[150:151], v[150:151], s[98:99], v[56:57]
	v_exp_f32_e32 v144, v144
	v_exp_f32_e32 v145, v145
	v_exp_f32_e32 v146, v146
	v_exp_f32_e32 v147, v147
	v_exp_f32_e32 v148, v148
	v_exp_f32_e32 v149, v149
	v_exp_f32_e32 v150, v150
	v_exp_f32_e32 v151, v151
	v_pk_add_f32 v[144:145], v[144:145], 1.0 op_sel_hi:[1,0]
	v_pk_add_f32 v[146:147], v[146:147], 1.0 op_sel_hi:[1,0]
	v_pk_add_f32 v[148:149], v[148:149], 1.0 op_sel_hi:[1,0]
	v_pk_add_f32 v[150:151], v[150:151], 1.0 op_sel_hi:[1,0]
	v_rcp_f32_e32 v144, v144
	v_rcp_f32_e32 v145, v145
	v_rcp_f32_e32 v146, v146
	v_rcp_f32_e32 v147, v147
	v_rcp_f32_e32 v148, v148
	v_rcp_f32_e32 v149, v149
	v_rcp_f32_e32 v150, v150
	v_rcp_f32_e32 v151, v151

.LBB0_177:
	s_and_b64 vcc, exec, s[40:41]
	s_cbranch_vccnz .LBB0_179
	s_waitcnt lgkmcnt(0)
	v_pk_fma_f32 v[102:103], v[102:103], s[98:99], v[46:47]
	v_pk_fma_f32 v[110:111], v[110:111], s[98:99], v[42:43]
	v_pk_fma_f32 v[116:117], v[116:117], s[98:99], v[44:45]
	v_pk_fma_f32 v[118:119], v[118:119], s[98:99], v[40:41]
	v_exp_f32_e32 v102, v102
	v_exp_f32_e32 v103, v103
	v_exp_f32_e32 v110, v110
	v_exp_f32_e32 v111, v111
	v_exp_f32_e32 v116, v116
	v_exp_f32_e32 v117, v117
	v_exp_f32_e32 v118, v118
	v_exp_f32_e32 v119, v119
	v_pk_add_f32 v[102:103], v[102:103], 1.0 op_sel_hi:[1,0]
	v_pk_add_f32 v[110:111], v[110:111], 1.0 op_sel_hi:[1,0]
	v_pk_add_f32 v[116:117], v[116:117], 1.0 op_sel_hi:[1,0]
	v_pk_add_f32 v[118:119], v[118:119], 1.0 op_sel_hi:[1,0]
	v_rcp_f32_e32 v102, v102
	v_rcp_f32_e32 v103, v103
	v_rcp_f32_e32 v110, v110
	v_rcp_f32_e32 v111, v111
	v_rcp_f32_e32 v116, v116
	v_rcp_f32_e32 v117, v117
	v_rcp_f32_e32 v118, v118
	v_rcp_f32_e32 v119, v119

.LBB0_189:
	s_and_b64 vcc, exec, s[40:41]
	s_cbranch_vccnz .LBB0_191
	s_waitcnt lgkmcnt(0)
	v_pk_fma_f32 v[142:143], v[142:143], s[98:99], v[62:63]
	v_pk_fma_f32 v[224:225], v[224:225], s[98:99], v[58:59]
	v_pk_fma_f32 v[228:229], v[228:229], s[98:99], v[60:61]
	v_pk_fma_f32 v[230:231], v[230:231], s[98:99], v[56:57]
	v_exp_f32_e32 v142, v142
	v_exp_f32_e32 v143, v143
	v_exp_f32_e32 v224, v224
	v_exp_f32_e32 v225, v225
	v_exp_f32_e32 v228, v228
	v_exp_f32_e32 v229, v229
	v_exp_f32_e32 v230, v230
	v_exp_f32_e32 v231, v231
	v_pk_add_f32 v[142:143], v[142:143], 1.0 op_sel_hi:[1,0]
	v_pk_add_f32 v[224:225], v[224:225], 1.0 op_sel_hi:[1,0]
	v_pk_add_f32 v[228:229], v[228:229], 1.0 op_sel_hi:[1,0]
	v_pk_add_f32 v[230:231], v[230:231], 1.0 op_sel_hi:[1,0]
	v_rcp_f32_e32 v142, v142
	v_rcp_f32_e32 v143, v143
	v_rcp_f32_e32 v224, v224
	v_rcp_f32_e32 v225, v225
	v_rcp_f32_e32 v228, v228
	v_rcp_f32_e32 v229, v229
	v_rcp_f32_e32 v230, v230
	v_rcp_f32_e32 v231, v231

.LBB0_199:
	s_and_b64 vcc, exec, s[40:41]
	s_cbranch_vccnz .LBB0_201
	s_waitcnt lgkmcnt(0)
	v_pk_fma_f32 v[134:135], v[134:135], s[98:99], v[46:47]
	v_pk_fma_f32 v[138:139], v[138:139], s[98:99], v[42:43]
	v_pk_fma_f32 v[140:141], v[140:141], s[98:99], v[44:45]
	v_pk_fma_f32 v[142:143], v[142:143], s[98:99], v[40:41]
	v_exp_f32_e32 v134, v134
	v_exp_f32_e32 v135, v135
	v_exp_f32_e32 v138, v138
	v_exp_f32_e32 v139, v139
	v_exp_f32_e32 v140, v140
	v_exp_f32_e32 v141, v141
	v_exp_f32_e32 v142, v142
	v_exp_f32_e32 v143, v143
	v_pk_add_f32 v[134:135], v[134:135], 1.0 op_sel_hi:[1,0]
	v_pk_add_f32 v[138:139], v[138:139], 1.0 op_sel_hi:[1,0]
	v_pk_add_f32 v[140:141], v[140:141], 1.0 op_sel_hi:[1,0]
	v_pk_add_f32 v[142:143], v[142:143], 1.0 op_sel_hi:[1,0]
	v_rcp_f32_e32 v134, v134
	v_rcp_f32_e32 v135, v135
	v_rcp_f32_e32 v138, v138
	v_rcp_f32_e32 v139, v139
	v_rcp_f32_e32 v140, v140
	v_rcp_f32_e32 v141, v141
	v_rcp_f32_e32 v142, v142
	v_rcp_f32_e32 v143, v143

.LBB0_209:
	s_and_b64 vcc, exec, s[40:41]
	s_cbranch_vccnz .LBB0_211
	s_waitcnt lgkmcnt(0)
	v_pk_fma_f32 v[94:95], v[94:95], s[98:99], v[62:63]
	v_pk_fma_f32 v[128:129], v[128:129], s[98:99], v[58:59]
	v_pk_fma_f32 v[130:131], v[130:131], s[98:99], v[60:61]
	v_pk_fma_f32 v[132:133], v[132:133], s[98:99], v[56:57]
	v_exp_f32_e32 v94, v94
	v_exp_f32_e32 v95, v95
	v_exp_f32_e32 v128, v128
	v_exp_f32_e32 v129, v129
	v_exp_f32_e32 v130, v130
	v_exp_f32_e32 v131, v131
	v_exp_f32_e32 v132, v132
	v_exp_f32_e32 v133, v133
	v_pk_add_f32 v[94:95], v[94:95], 1.0 op_sel_hi:[1,0]
	v_pk_add_f32 v[128:129], v[128:129], 1.0 op_sel_hi:[1,0]
	v_pk_add_f32 v[130:131], v[130:131], 1.0 op_sel_hi:[1,0]
	v_pk_add_f32 v[132:133], v[132:133], 1.0 op_sel_hi:[1,0]
	v_rcp_f32_e32 v94, v94
	v_rcp_f32_e32 v95, v95
	v_rcp_f32_e32 v128, v128
	v_rcp_f32_e32 v129, v129
	v_rcp_f32_e32 v130, v130
	v_rcp_f32_e32 v131, v131
	v_rcp_f32_e32 v132, v132
	v_rcp_f32_e32 v133, v133

.LBB0_219:
	s_and_b64 vcc, exec, s[40:41]
	s_cbranch_vccnz .LBB0_221
	s_waitcnt lgkmcnt(0)
	v_pk_fma_f32 v[86:87], v[86:87], s[98:99], v[46:47]
	v_pk_fma_f32 v[90:91], v[90:91], s[98:99], v[42:43]
	v_pk_fma_f32 v[92:93], v[92:93], s[98:99], v[44:45]
	v_pk_fma_f32 v[94:95], v[94:95], s[98:99], v[40:41]
	v_exp_f32_e32 v86, v86
	v_exp_f32_e32 v87, v87
	v_exp_f32_e32 v90, v90
	v_exp_f32_e32 v91, v91
	v_exp_f32_e32 v92, v92
	v_exp_f32_e32 v93, v93
	v_exp_f32_e32 v94, v94
	v_exp_f32_e32 v95, v95
	v_pk_add_f32 v[86:87], v[86:87], 1.0 op_sel_hi:[1,0]
	v_pk_add_f32 v[90:91], v[90:91], 1.0 op_sel_hi:[1,0]
	v_pk_add_f32 v[92:93], v[92:93], 1.0 op_sel_hi:[1,0]
	v_pk_add_f32 v[94:95], v[94:95], 1.0 op_sel_hi:[1,0]
	v_rcp_f32_e32 v86, v86
	v_rcp_f32_e32 v87, v87
	v_rcp_f32_e32 v90, v90
	v_rcp_f32_e32 v91, v91
	v_rcp_f32_e32 v92, v92
	v_rcp_f32_e32 v93, v93
	v_rcp_f32_e32 v94, v94
	v_rcp_f32_e32 v95, v95

.LBB0_231:
	s_and_b64 vcc, exec, s[40:41]
	s_cbranch_vccnz .LBB0_233
	s_waitcnt lgkmcnt(0)
	v_pk_fma_f32 v[78:79], v[78:79], s[98:99], v[62:63]
	v_pk_fma_f32 v[82:83], v[82:83], s[98:99], v[58:59]
	v_pk_fma_f32 v[84:85], v[84:85], s[98:99], v[60:61]
	v_pk_fma_f32 v[86:87], v[86:87], s[98:99], v[56:57]
	v_exp_f32_e32 v78, v78
	v_exp_f32_e32 v79, v79
	v_exp_f32_e32 v82, v82
	v_exp_f32_e32 v83, v83
	v_exp_f32_e32 v84, v84
	v_exp_f32_e32 v85, v85
	v_exp_f32_e32 v86, v86
	v_exp_f32_e32 v87, v87
	v_pk_add_f32 v[78:79], v[78:79], 1.0 op_sel_hi:[1,0]
	v_pk_add_f32 v[82:83], v[82:83], 1.0 op_sel_hi:[1,0]
	v_pk_add_f32 v[84:85], v[84:85], 1.0 op_sel_hi:[1,0]
	v_pk_add_f32 v[86:87], v[86:87], 1.0 op_sel_hi:[1,0]
	v_rcp_f32_e32 v78, v78
	v_rcp_f32_e32 v79, v79
	v_rcp_f32_e32 v82, v82
	v_rcp_f32_e32 v83, v83
	v_rcp_f32_e32 v84, v84
	v_rcp_f32_e32 v85, v85
	v_rcp_f32_e32 v86, v86
	v_rcp_f32_e32 v87, v87

.LBB0_241:
	s_and_b64 vcc, exec, s[40:41]
	s_cbranch_vccnz .LBB0_243
	s_waitcnt lgkmcnt(0)
	v_pk_fma_f32 v[70:71], v[70:71], s[98:99], v[46:47]
	v_pk_fma_f32 v[74:75], v[74:75], s[98:99], v[42:43]
	v_pk_fma_f32 v[76:77], v[76:77], s[98:99], v[44:45]
	v_pk_fma_f32 v[78:79], v[78:79], s[98:99], v[40:41]
	v_exp_f32_e32 v70, v70
	v_exp_f32_e32 v71, v71
	v_exp_f32_e32 v74, v74
	v_exp_f32_e32 v75, v75
	v_exp_f32_e32 v76, v76
	v_exp_f32_e32 v77, v77
	v_exp_f32_e32 v78, v78
	v_exp_f32_e32 v79, v79
	v_pk_add_f32 v[70:71], v[70:71], 1.0 op_sel_hi:[1,0]
	v_pk_add_f32 v[74:75], v[74:75], 1.0 op_sel_hi:[1,0]
	v_pk_add_f32 v[76:77], v[76:77], 1.0 op_sel_hi:[1,0]
	v_pk_add_f32 v[78:79], v[78:79], 1.0 op_sel_hi:[1,0]
	v_rcp_f32_e32 v70, v70
	v_rcp_f32_e32 v71, v71
	v_rcp_f32_e32 v74, v74
	v_rcp_f32_e32 v75, v75
	v_rcp_f32_e32 v76, v76
	v_rcp_f32_e32 v77, v77
	v_rcp_f32_e32 v78, v78
	v_rcp_f32_e32 v79, v79

.LBB0_251:
	s_and_b64 vcc, exec, s[40:41]
	s_cbranch_vccnz .LBB0_253
	s_waitcnt lgkmcnt(0)
	v_pk_fma_f32 v[54:55], v[54:55], s[98:99], v[62:63]
	v_pk_fma_f32 v[64:65], v[64:65], s[98:99], v[58:59]
	v_pk_fma_f32 v[66:67], v[66:67], s[98:99], v[60:61]
	v_pk_fma_f32 v[68:69], v[68:69], s[98:99], v[56:57]
	v_exp_f32_e32 v54, v54
	v_exp_f32_e32 v55, v55
	v_exp_f32_e32 v64, v64
	v_exp_f32_e32 v65, v65
	v_exp_f32_e32 v66, v66
	v_exp_f32_e32 v67, v67
	v_exp_f32_e32 v68, v68
	v_exp_f32_e32 v69, v69
	v_pk_add_f32 v[54:55], v[54:55], 1.0 op_sel_hi:[1,0]
	v_pk_add_f32 v[64:65], v[64:65], 1.0 op_sel_hi:[1,0]
	v_pk_add_f32 v[66:67], v[66:67], 1.0 op_sel_hi:[1,0]
	v_pk_add_f32 v[68:69], v[68:69], 1.0 op_sel_hi:[1,0]
	v_rcp_f32_e32 v54, v54
	v_rcp_f32_e32 v55, v55
	v_rcp_f32_e32 v64, v64
	v_rcp_f32_e32 v65, v65
	v_rcp_f32_e32 v66, v66
	v_rcp_f32_e32 v67, v67
	v_rcp_f32_e32 v68, v68
	v_rcp_f32_e32 v69, v69

.LBB0_261:
	s_and_b64 vcc, exec, s[40:41]
	s_cbranch_vccnz .LBB0_263
	s_waitcnt lgkmcnt(0)
	v_pk_fma_f32 v[38:39], v[38:39], s[98:99], v[46:47]
	v_pk_fma_f32 v[50:51], v[50:51], s[98:99], v[42:43]
	v_pk_fma_f32 v[52:53], v[52:53], s[98:99], v[44:45]
	v_pk_fma_f32 v[54:55], v[54:55], s[98:99], v[40:41]
	v_exp_f32_e32 v38, v38
	v_exp_f32_e32 v39, v39
	v_exp_f32_e32 v50, v50
	v_exp_f32_e32 v51, v51
	v_exp_f32_e32 v52, v52
	v_exp_f32_e32 v53, v53
	v_exp_f32_e32 v54, v54
	v_exp_f32_e32 v55, v55
	v_pk_add_f32 v[38:39], v[38:39], 1.0 op_sel_hi:[1,0]
	v_pk_add_f32 v[50:51], v[50:51], 1.0 op_sel_hi:[1,0]
	v_pk_add_f32 v[52:53], v[52:53], 1.0 op_sel_hi:[1,0]
	v_pk_add_f32 v[54:55], v[54:55], 1.0 op_sel_hi:[1,0]
	v_rcp_f32_e32 v38, v38
	v_rcp_f32_e32 v39, v39
	v_rcp_f32_e32 v50, v50
	v_rcp_f32_e32 v51, v51
	v_rcp_f32_e32 v52, v52
	v_rcp_f32_e32 v53, v53
	v_rcp_f32_e32 v54, v54
	v_rcp_f32_e32 v55, v55

.LBB0_273:
	s_and_b64 vcc, exec, s[40:41]
	s_cbranch_vccnz .LBB0_275
	s_waitcnt lgkmcnt(0)
	v_pk_fma_f32 v[30:31], v[30:31], s[98:99], v[62:63]
	v_pk_fma_f32 v[32:33], v[32:33], s[98:99], v[58:59]
	v_pk_fma_f32 v[34:35], v[34:35], s[98:99], v[60:61]
	v_pk_fma_f32 v[36:37], v[36:37], s[98:99], v[56:57]
	v_exp_f32_e32 v30, v30
	v_exp_f32_e32 v31, v31
	v_exp_f32_e32 v32, v32
	v_exp_f32_e32 v33, v33
	v_exp_f32_e32 v34, v34
	v_exp_f32_e32 v35, v35
	v_exp_f32_e32 v36, v36
	v_exp_f32_e32 v37, v37
	v_pk_add_f32 v[30:31], v[30:31], 1.0 op_sel_hi:[1,0]
	v_pk_add_f32 v[32:33], v[32:33], 1.0 op_sel_hi:[1,0]
	v_pk_add_f32 v[34:35], v[34:35], 1.0 op_sel_hi:[1,0]
	v_pk_add_f32 v[36:37], v[36:37], 1.0 op_sel_hi:[1,0]
	v_rcp_f32_e32 v30, v30
	v_rcp_f32_e32 v31, v31
	v_rcp_f32_e32 v32, v32
	v_rcp_f32_e32 v33, v33
	v_rcp_f32_e32 v34, v34
	v_rcp_f32_e32 v35, v35
	v_rcp_f32_e32 v36, v36
	v_rcp_f32_e32 v37, v37

.LBB0_283:
	s_and_b64 vcc, exec, s[40:41]
	s_cbranch_vccnz .LBB0_285
	s_waitcnt lgkmcnt(0)
	v_pk_fma_f32 v[22:23], v[22:23], s[98:99], v[46:47]
	v_pk_fma_f32 v[26:27], v[26:27], s[98:99], v[42:43]
	v_pk_fma_f32 v[28:29], v[28:29], s[98:99], v[44:45]
	v_pk_fma_f32 v[30:31], v[30:31], s[98:99], v[40:41]
	v_exp_f32_e32 v22, v22
	v_exp_f32_e32 v23, v23
	v_exp_f32_e32 v26, v26
	v_exp_f32_e32 v27, v27
	v_exp_f32_e32 v28, v28
	v_exp_f32_e32 v29, v29
	v_exp_f32_e32 v30, v30
	v_exp_f32_e32 v31, v31
	v_pk_add_f32 v[22:23], v[22:23], 1.0 op_sel_hi:[1,0]
	v_pk_add_f32 v[26:27], v[26:27], 1.0 op_sel_hi:[1,0]
	v_pk_add_f32 v[28:29], v[28:29], 1.0 op_sel_hi:[1,0]
	v_pk_add_f32 v[30:31], v[30:31], 1.0 op_sel_hi:[1,0]
	v_rcp_f32_e32 v22, v22
	v_rcp_f32_e32 v23, v23
	v_rcp_f32_e32 v26, v26
	v_rcp_f32_e32 v27, v27
	v_rcp_f32_e32 v28, v28
	v_rcp_f32_e32 v29, v29
	v_rcp_f32_e32 v30, v30
	v_rcp_f32_e32 v31, v31

.LBB0_293:
	s_and_b64 vcc, exec, s[40:41]
	s_cbranch_vccnz .LBB0_295
	s_waitcnt lgkmcnt(0)
	v_pk_fma_f32 v[14:15], v[14:15], s[98:99], v[62:63]
	v_pk_fma_f32 v[16:17], v[16:17], s[98:99], v[58:59]
	v_pk_fma_f32 v[18:19], v[18:19], s[98:99], v[60:61]
	v_pk_fma_f32 v[20:21], v[20:21], s[98:99], v[56:57]
	v_exp_f32_e32 v14, v14
	v_exp_f32_e32 v15, v15
	v_exp_f32_e32 v16, v16
	v_exp_f32_e32 v17, v17
	v_exp_f32_e32 v18, v18
	v_exp_f32_e32 v19, v19
	v_exp_f32_e32 v20, v20
	v_exp_f32_e32 v21, v21
	v_pk_add_f32 v[14:15], v[14:15], 1.0 op_sel_hi:[1,0]
	v_pk_add_f32 v[16:17], v[16:17], 1.0 op_sel_hi:[1,0]
	v_pk_add_f32 v[18:19], v[18:19], 1.0 op_sel_hi:[1,0]
	v_pk_add_f32 v[20:21], v[20:21], 1.0 op_sel_hi:[1,0]
	v_rcp_f32_e32 v14, v14
	v_rcp_f32_e32 v15, v15
	v_rcp_f32_e32 v16, v16
	v_rcp_f32_e32 v17, v17
	v_rcp_f32_e32 v18, v18
	v_rcp_f32_e32 v19, v19
	v_rcp_f32_e32 v20, v20
	v_rcp_f32_e32 v21, v21

.LBB0_303:
	s_and_b64 vcc, exec, s[40:41]
	s_cbranch_vccnz .LBB0_305
	s_waitcnt lgkmcnt(0)
	v_pk_fma_f32 v[6:7], v[6:7], s[98:99], v[46:47]
	v_pk_fma_f32 v[10:11], v[10:11], s[98:99], v[42:43]
	v_pk_fma_f32 v[12:13], v[12:13], s[98:99], v[44:45]
	v_pk_fma_f32 v[14:15], v[14:15], s[98:99], v[40:41]
	v_exp_f32_e32 v6, v6
	v_exp_f32_e32 v7, v7
	v_exp_f32_e32 v10, v10
	v_exp_f32_e32 v11, v11
	v_exp_f32_e32 v12, v12
	v_exp_f32_e32 v13, v13
	v_exp_f32_e32 v14, v14
	v_exp_f32_e32 v15, v15
	v_pk_add_f32 v[6:7], v[6:7], 1.0 op_sel_hi:[1,0]
	v_pk_add_f32 v[10:11], v[10:11], 1.0 op_sel_hi:[1,0]
	v_pk_add_f32 v[12:13], v[12:13], 1.0 op_sel_hi:[1,0]
	v_pk_add_f32 v[14:15], v[14:15], 1.0 op_sel_hi:[1,0]
	v_rcp_f32_e32 v6, v6
	v_rcp_f32_e32 v7, v7
	v_rcp_f32_e32 v10, v10
	v_rcp_f32_e32 v11, v11
	v_rcp_f32_e32 v12, v12
	v_rcp_f32_e32 v13, v13
	v_rcp_f32_e32 v14, v14
	v_rcp_f32_e32 v15, v15
